# attention unit prologue: the 7 serialized relative-position-bias loads (load, wait, LDS write each) issued together with one wait
# speedup vs baseline: 1.0572x; 1.0017x over previous
; __device__ __forceinline__ void attn_unit(int u, const bf16_t* QB, const bf16_t* KB, const bf16_t* VTL, const bf16_t* VTC, const float* rpb, bf16_t* MIX, LAS float* rl, int lane) {
;     ...
;     for (int i = lane; i < 465; i += 64) { const int ro = i / 31, co = i - ro * 31; rl[ro * 32 + co] = rpb[h * 465 + i]; }
;     asm volatile("s_waitcnt lgkmcnt(0)" ::: "memory");
.LBB0_682:
	v_bfe_u32 v2, v181, 6, 3
	v_mul_u32_u24_e32 v0, 0x1d1, v2
	v_readlane_b32 s52, v253, 0
	v_add_lshl_u32 v0, v178, v0, 2
	v_readlane_b32 s64, v253, 12
	v_readlane_b32 s65, v253, 13
	v_readlane_b32 s53, v253, 1
	v_readlane_b32 s54, v253, 2
	v_readlane_b32 s55, v253, 3
	v_readlane_b32 s56, v253, 4
	v_readlane_b32 s57, v253, 5
	global_load_dword v3, v0, s[64:65]
	global_load_dword v240, v0, s[64:65] offset:256
	global_load_dword v241, v0, s[64:65] offset:512
	global_load_dword v242, v0, s[64:65] offset:768
	global_load_dword v243, v0, s[64:65] offset:1024
	global_load_dword v244, v0, s[64:65] offset:1280
	global_load_dword v245, v0, s[64:65] offset:1536
	v_readlane_b32 s58, v253, 6
	v_readlane_b32 s59, v253, 7
	v_readlane_b32 s60, v253, 8
	v_readlane_b32 s61, v253, 9
	v_readlane_b32 s62, v253, 10
	v_readlane_b32 s63, v253, 11
	v_readlane_b32 s66, v253, 14
	v_readlane_b32 s67, v253, 15
	s_waitcnt vmcnt(0)
	ds_write_b32 v165, v3 offset:40960
	ds_write_b32 v179, v240 offset:41216
	ds_write_b32 v188, v241 offset:41472
	ds_write_b32 v189, v242 offset:41728
	ds_write_b32 v190, v243 offset:41984
	ds_write_b32 v191, v244 offset:42240
	ds_write_b32 v192, v245 offset:42496
	s_mov_b64 s[44:45], exec
	v_readlane_b32 s50, v252, 29
	v_readlane_b32 s51, v252, 30
	s_and_b64 s[50:51], s[44:45], s[50:51]
	s_mov_b64 exec, s[50:51]
	s_cbranch_execz .LBB0_684
	v_readlane_b32 s52, v253, 0
	v_readlane_b32 s64, v253, 12
	v_readlane_b32 s65, v253, 13
	v_readlane_b32 s53, v253, 1
	v_readlane_b32 s54, v253, 2
	v_lshl_add_u64 v[4:5], s[64:65], 0, v[0:1]
	global_load_dword v0, v[4:5], off offset:1792
	v_readlane_b32 s55, v253, 3
	v_readlane_b32 s56, v253, 4
	v_readlane_b32 s57, v253, 5
	v_readlane_b32 s58, v253, 6
	v_readlane_b32 s59, v253, 7
	v_readlane_b32 s60, v253, 8
	v_readlane_b32 s61, v253, 9
	v_readlane_b32 s62, v253, 10
	v_readlane_b32 s63, v253, 11
	v_readlane_b32 s66, v253, 14
	v_readlane_b32 s67, v253, 15
	s_waitcnt vmcnt(0)
	ds_write_b32 v193, v0 offset:42752
